# grid barrier: XCD last arriver skips the per-XCD relay atomic (no workgroup polls it after the flat-poll change) and its completion wait
# baseline (speedup 1.0000x reference)
; DI unsigned xb_ld(unsigned* p) { return __hip_atomic_load(p, __ATOMIC_RELAXED, __HIP_MEMORY_SCOPE_AGENT); }
; DI unsigned xb_add(unsigned* p, unsigned v) { return __hip_atomic_fetch_add(p, v, __ATOMIC_RELAXED, __HIP_MEMORY_SCOPE_AGENT); }
; DI void xcd_barrier(const XcdBarrier& b) {
;     ...
;       if (og + 1u == (tg + 1u) * nx) xb_add(&bar[XB_TOPGEN], 1u);
;       else { while (xb_ld(&bar[XB_TOPGEN]) == tg) __builtin_amdgcn_s_sleep(1); }
;       __builtin_amdgcn_fence(__ATOMIC_ACQUIRE, "agent");
;       xb_add(&bar[XB_XGEN(bx)], 1u);
;       asm volatile("s_waitcnt vmcnt(0)" ::: "memory");
.LBB0_910:
	s_or_b64 exec, exec, s[2:3]
	s_mov_b64 s[2:3], exec
	v_mbcnt_lo_u32_b32 v0, s2, 0
	v_mbcnt_hi_u32_b32 v0, s3, v0
	v_cmp_eq_u32_e32 vcc, 0, v0
	s_waitcnt vmcnt(0)
	buffer_inv sc1
	s_and_saveexec_b64 s[4:5], vcc
	s_branch .LBB0_118
